# ffup epilogue: consumption of the first row block's LDS read-back deferred by one more group (more time to hide the LDS round trip)
# baseline (speedup 1.0000x reference)
.LBB0_1034:
	v_lshl_or_b32 v115, v183, 3, v191
	v_lshrrev_b32_e32 v116, 6, v115
	v_and_b32_e32 v117, 63, v115
	v_lshlrev_b32_e32 v113, 11, v116
	v_add_u32_e32 v113, 0x10000, v113
	v_readfirstlane_b32 s100, v116
	v_and_b32_e32 v112, 31, v117
	v_lshl_add_u32 v112, v112, 1, v113
	v_lshrrev_b32_e32 v116, 5, v117
	v_lshl_add_u32 v112, v116, 8, v112
	v_lshl_add_u32 v113, v117, 4, v113
	v_lshrrev_b32_e32 v116, 2, v117
	v_mul_u32_u24_e32 v116, 0x1600, v116
	v_and_b32_e32 v114, 3, v117
	v_lshl_add_u32 v114, v114, 4, v116
	s_lshr_b32 s101, s100, 1
	s_lshl_b32 s101, s101, 6
	s_add_u32 s101, s101, s48
	s_mul_i32 s101, s101, 0x1600
	s_and_b32 s100, s100, 1
	s_lshl_b32 s100, s100, 6
	s_add_u32 s100, s100, s49
	s_add_u32 s101, s101, s100
	s_add_u32 s98, s90, 0x3971900
	s_addc_u32 s99, s91, 0
	s_add_u32 s98, s98, s101
	s_addc_u32 s99, s99, 0
	v_mul_f32_e32 v64, 0xbfb8aa3b, v48
	v_mul_f32_e32 v70, 0xbfb8aa3b, v49
	v_mul_f32_e32 v76, 0xbfb8aa3b, v50
	v_mul_f32_e32 v82, 0xbfb8aa3b, v51
	v_exp_f32_e32 v64, v64
	v_exp_f32_e32 v70, v70
	v_exp_f32_e32 v76, v76
	v_exp_f32_e32 v82, v82
	v_add_f32_e32 v64, 1.0, v64
	v_add_f32_e32 v70, 1.0, v70
	v_add_f32_e32 v76, 1.0, v76
	v_add_f32_e32 v82, 1.0, v82
	v_div_scale_f32 v65, s[2:3], v64, v64, 1.0
	v_div_scale_f32 v71, s[2:3], v70, v70, 1.0
	v_div_scale_f32 v77, s[2:3], v76, v76, 1.0
	v_div_scale_f32 v83, s[2:3], v82, v82, 1.0
	v_rcp_f32_e32 v66, v65
	v_rcp_f32_e32 v72, v71
	v_rcp_f32_e32 v78, v77
	v_rcp_f32_e32 v84, v83
	v_fma_f32 v69, -v65, v66, 1.0
	v_fma_f32 v75, -v71, v72, 1.0
	v_fma_f32 v81, -v77, v78, 1.0
	v_fma_f32 v87, -v83, v84, 1.0
	v_fmac_f32_e32 v66, v69, v66
	v_fmac_f32_e32 v72, v75, v72
	v_fmac_f32_e32 v78, v81, v78
	v_fmac_f32_e32 v84, v87, v84
	v_div_scale_f32 v67, vcc, 1.0, v64, 1.0
	v_mul_f32_e32 v88, 0xbfb8aa3b, v52
	v_mul_f32_e32 v68, v67, v66
	v_mul_f32_e32 v94, 0xbfb8aa3b, v53
	v_fma_f32 v69, -v65, v68, v67
	v_mul_f32_e32 v100, 0xbfb8aa3b, v54
	v_fmac_f32_e32 v68, v69, v66
	v_mul_f32_e32 v106, 0xbfb8aa3b, v55
	v_fma_f32 v65, -v65, v68, v67
	v_exp_f32_e32 v88, v88
	v_div_fmas_f32 v65, v65, v66, v68
	v_exp_f32_e32 v94, v94
	v_div_scale_f32 v73, vcc, 1.0, v70, 1.0
	v_exp_f32_e32 v100, v100
	v_mul_f32_e32 v74, v73, v72
	v_exp_f32_e32 v106, v106
	v_fma_f32 v75, -v71, v74, v73
	v_add_f32_e32 v88, 1.0, v88
	v_fmac_f32_e32 v74, v75, v72
	v_add_f32_e32 v94, 1.0, v94
	v_fma_f32 v71, -v71, v74, v73
	v_add_f32_e32 v100, 1.0, v100
	v_div_fmas_f32 v71, v71, v72, v74
	v_add_f32_e32 v106, 1.0, v106
	v_div_scale_f32 v79, vcc, 1.0, v76, 1.0
	v_div_scale_f32 v89, s[2:3], v88, v88, 1.0
	v_mul_f32_e32 v80, v79, v78
	v_div_scale_f32 v95, s[2:3], v94, v94, 1.0
	v_fma_f32 v81, -v77, v80, v79
	v_div_scale_f32 v101, s[2:3], v100, v100, 1.0
	v_fmac_f32_e32 v80, v81, v78
	v_div_scale_f32 v107, s[2:3], v106, v106, 1.0
	v_fma_f32 v77, -v77, v80, v79
	v_rcp_f32_e32 v90, v89
	v_div_fmas_f32 v77, v77, v78, v80
	v_rcp_f32_e32 v96, v95
	v_div_scale_f32 v85, vcc, 1.0, v82, 1.0
	v_rcp_f32_e32 v102, v101
	v_mul_f32_e32 v86, v85, v84
	v_rcp_f32_e32 v108, v107
	v_fma_f32 v87, -v83, v86, v85
	v_fma_f32 v93, -v89, v90, 1.0
	v_fmac_f32_e32 v86, v87, v84
	v_fma_f32 v99, -v95, v96, 1.0
	v_fma_f32 v83, -v83, v86, v85
	v_fma_f32 v105, -v101, v102, 1.0
	v_div_fmas_f32 v83, v83, v84, v86
	v_fma_f32 v111, -v107, v108, 1.0
	v_fmac_f32_e32 v90, v93, v90
	v_fmac_f32_e32 v96, v99, v96
	v_fmac_f32_e32 v102, v105, v102
	v_fmac_f32_e32 v108, v111, v108
	v_div_fixup_f32 v65, v65, v64, 1.0
	v_div_fixup_f32 v71, v71, v70, 1.0
	v_div_fixup_f32 v77, v77, v76, 1.0
	v_div_fixup_f32 v83, v83, v82, 1.0
	v_mul_f32_e32 v65, v48, v65
	v_mul_f32_e32 v71, v49, v71
	v_mul_f32_e32 v77, v50, v77
	v_mul_f32_e32 v83, v51, v83
	v_mul_f32_e32 v65, v32, v65
	v_mul_f32_e32 v71, v33, v71
	v_mul_f32_e32 v77, v34, v77
	v_mul_f32_e32 v83, v35, v83
	v_cvt_pk_bf16_f32 v65, v65, v65
	v_cvt_pk_bf16_f32 v71, v71, v71
	v_cvt_pk_bf16_f32 v77, v77, v77
	v_cvt_pk_bf16_f32 v83, v83, v83
	ds_write_b16 v112, v65
	ds_write_b16 v112, v71 offset:64
	ds_write_b16 v112, v77 offset:128
	ds_write_b16 v112, v83 offset:192
	v_div_scale_f32 v91, vcc, 1.0, v88, 1.0
	v_mul_f32_e32 v64, 0xbfb8aa3b, v56
	v_mul_f32_e32 v92, v91, v90
	v_mul_f32_e32 v70, 0xbfb8aa3b, v57
	v_fma_f32 v93, -v89, v92, v91
	v_mul_f32_e32 v76, 0xbfb8aa3b, v58
	v_fmac_f32_e32 v92, v93, v90
	v_mul_f32_e32 v82, 0xbfb8aa3b, v59
	v_fma_f32 v89, -v89, v92, v91
	v_exp_f32_e32 v64, v64
	v_div_fmas_f32 v89, v89, v90, v92
	v_exp_f32_e32 v70, v70
	v_div_scale_f32 v97, vcc, 1.0, v94, 1.0
	v_exp_f32_e32 v76, v76
	v_mul_f32_e32 v98, v97, v96
	v_exp_f32_e32 v82, v82
	v_fma_f32 v99, -v95, v98, v97
	v_add_f32_e32 v64, 1.0, v64
	v_fmac_f32_e32 v98, v99, v96
	v_add_f32_e32 v70, 1.0, v70
	v_fma_f32 v95, -v95, v98, v97
	v_add_f32_e32 v76, 1.0, v76
	v_div_fmas_f32 v95, v95, v96, v98
	v_add_f32_e32 v82, 1.0, v82
	v_div_scale_f32 v103, vcc, 1.0, v100, 1.0
	v_div_scale_f32 v65, s[2:3], v64, v64, 1.0
	v_mul_f32_e32 v104, v103, v102
	v_div_scale_f32 v71, s[2:3], v70, v70, 1.0
	v_fma_f32 v105, -v101, v104, v103
	v_div_scale_f32 v77, s[2:3], v76, v76, 1.0
	v_fmac_f32_e32 v104, v105, v102
	v_div_scale_f32 v83, s[2:3], v82, v82, 1.0
	v_fma_f32 v101, -v101, v104, v103
	v_rcp_f32_e32 v66, v65
	v_div_fmas_f32 v101, v101, v102, v104
	v_rcp_f32_e32 v72, v71
	v_div_scale_f32 v109, vcc, 1.0, v106, 1.0
	v_rcp_f32_e32 v78, v77
	v_mul_f32_e32 v110, v109, v108
	v_rcp_f32_e32 v84, v83
	v_fma_f32 v111, -v107, v110, v109
	v_fma_f32 v69, -v65, v66, 1.0
	v_fmac_f32_e32 v110, v111, v108
	v_fma_f32 v75, -v71, v72, 1.0
	v_fma_f32 v107, -v107, v110, v109
	v_fma_f32 v81, -v77, v78, 1.0
	v_div_fmas_f32 v107, v107, v108, v110
	v_fma_f32 v87, -v83, v84, 1.0
	v_fmac_f32_e32 v66, v69, v66
	v_fmac_f32_e32 v72, v75, v72
	v_fmac_f32_e32 v78, v81, v78
	v_fmac_f32_e32 v84, v87, v84
	v_div_fixup_f32 v89, v89, v88, 1.0
	v_div_fixup_f32 v95, v95, v94, 1.0
	v_div_fixup_f32 v101, v101, v100, 1.0
	v_div_fixup_f32 v107, v107, v106, 1.0
	v_mul_f32_e32 v89, v52, v89
	v_mul_f32_e32 v95, v53, v95
	v_mul_f32_e32 v101, v54, v101
	v_mul_f32_e32 v107, v55, v107
	v_mul_f32_e32 v89, v36, v89
	v_mul_f32_e32 v95, v37, v95
	v_mul_f32_e32 v101, v38, v101
	v_mul_f32_e32 v107, v39, v107
	v_cvt_pk_bf16_f32 v89, v89, v89
	v_cvt_pk_bf16_f32 v95, v95, v95
	v_cvt_pk_bf16_f32 v101, v101, v101
	v_cvt_pk_bf16_f32 v107, v107, v107
	ds_write_b16 v112, v89 offset:512
	ds_write_b16 v112, v95 offset:576
	ds_write_b16 v112, v101 offset:640
	ds_write_b16 v112, v107 offset:704
	v_div_scale_f32 v67, vcc, 1.0, v64, 1.0
	v_mul_f32_e32 v88, 0xbfb8aa3b, v60
	v_mul_f32_e32 v68, v67, v66
	v_mul_f32_e32 v94, 0xbfb8aa3b, v61
	v_fma_f32 v69, -v65, v68, v67
	v_mul_f32_e32 v100, 0xbfb8aa3b, v62
	v_fmac_f32_e32 v68, v69, v66
	v_mul_f32_e32 v106, 0xbfb8aa3b, v63
	v_fma_f32 v65, -v65, v68, v67
	v_exp_f32_e32 v88, v88
	v_div_fmas_f32 v65, v65, v66, v68
	v_exp_f32_e32 v94, v94
	v_div_scale_f32 v73, vcc, 1.0, v70, 1.0
	v_exp_f32_e32 v100, v100
	v_mul_f32_e32 v74, v73, v72
	v_exp_f32_e32 v106, v106
	v_fma_f32 v75, -v71, v74, v73
	v_add_f32_e32 v88, 1.0, v88
	v_fmac_f32_e32 v74, v75, v72
	v_add_f32_e32 v94, 1.0, v94
	v_fma_f32 v71, -v71, v74, v73
	v_add_f32_e32 v100, 1.0, v100
	v_div_fmas_f32 v71, v71, v72, v74
	v_add_f32_e32 v106, 1.0, v106
	v_div_scale_f32 v79, vcc, 1.0, v76, 1.0
	v_div_scale_f32 v89, s[2:3], v88, v88, 1.0
	v_mul_f32_e32 v80, v79, v78
	v_div_scale_f32 v95, s[2:3], v94, v94, 1.0
	v_fma_f32 v81, -v77, v80, v79
	v_div_scale_f32 v101, s[2:3], v100, v100, 1.0
	v_fmac_f32_e32 v80, v81, v78
	v_div_scale_f32 v107, s[2:3], v106, v106, 1.0
	v_fma_f32 v77, -v77, v80, v79
	v_rcp_f32_e32 v90, v89
	v_div_fmas_f32 v77, v77, v78, v80
	v_rcp_f32_e32 v96, v95
	v_div_scale_f32 v85, vcc, 1.0, v82, 1.0
	v_rcp_f32_e32 v102, v101
	v_mul_f32_e32 v86, v85, v84
	v_rcp_f32_e32 v108, v107
	v_fma_f32 v87, -v83, v86, v85
	v_fma_f32 v93, -v89, v90, 1.0
	v_fmac_f32_e32 v86, v87, v84
	v_fma_f32 v99, -v95, v96, 1.0
	v_fma_f32 v83, -v83, v86, v85
	v_fma_f32 v105, -v101, v102, 1.0
	v_div_fmas_f32 v83, v83, v84, v86
	v_fma_f32 v111, -v107, v108, 1.0
	v_fmac_f32_e32 v90, v93, v90
	v_fmac_f32_e32 v96, v99, v96
	v_fmac_f32_e32 v102, v105, v102
	v_fmac_f32_e32 v108, v111, v108
	v_div_fixup_f32 v65, v65, v64, 1.0
	v_div_fixup_f32 v71, v71, v70, 1.0
	v_div_fixup_f32 v77, v77, v76, 1.0
	v_div_fixup_f32 v83, v83, v82, 1.0
	v_mul_f32_e32 v65, v56, v65
	v_mul_f32_e32 v71, v57, v71
	v_mul_f32_e32 v77, v58, v77
	v_mul_f32_e32 v83, v59, v83
	v_mul_f32_e32 v65, v40, v65
	v_mul_f32_e32 v71, v41, v71
	v_mul_f32_e32 v77, v42, v77
	v_mul_f32_e32 v83, v43, v83
	v_cvt_pk_bf16_f32 v65, v65, v65
	v_cvt_pk_bf16_f32 v71, v71, v71
	v_cvt_pk_bf16_f32 v77, v77, v77
	v_cvt_pk_bf16_f32 v83, v83, v83
	ds_write_b16 v112, v65 offset:1024
	ds_write_b16 v112, v71 offset:1088
	ds_write_b16 v112, v77 offset:1152
	ds_write_b16 v112, v83 offset:1216
	v_div_scale_f32 v91, vcc, 1.0, v88, 1.0
	v_mul_f32_e32 v64, 0xbfb8aa3b, v16
	v_mul_f32_e32 v92, v91, v90
	v_mul_f32_e32 v70, 0xbfb8aa3b, v17
	v_fma_f32 v93, -v89, v92, v91
	v_mul_f32_e32 v76, 0xbfb8aa3b, v18
	v_fmac_f32_e32 v92, v93, v90
	v_mul_f32_e32 v82, 0xbfb8aa3b, v19
	v_fma_f32 v89, -v89, v92, v91
	v_exp_f32_e32 v64, v64
	v_div_fmas_f32 v89, v89, v90, v92
	v_exp_f32_e32 v70, v70
	v_div_scale_f32 v97, vcc, 1.0, v94, 1.0
	v_exp_f32_e32 v76, v76
	v_mul_f32_e32 v98, v97, v96
	v_exp_f32_e32 v82, v82
	v_fma_f32 v99, -v95, v98, v97
	v_add_f32_e32 v64, 1.0, v64
	v_fmac_f32_e32 v98, v99, v96
	v_add_f32_e32 v70, 1.0, v70
	v_fma_f32 v95, -v95, v98, v97
	v_add_f32_e32 v76, 1.0, v76
	v_div_fmas_f32 v95, v95, v96, v98
	v_add_f32_e32 v82, 1.0, v82
	v_div_scale_f32 v103, vcc, 1.0, v100, 1.0
	v_div_scale_f32 v65, s[2:3], v64, v64, 1.0
	v_mul_f32_e32 v104, v103, v102
	v_div_scale_f32 v71, s[2:3], v70, v70, 1.0
	v_fma_f32 v105, -v101, v104, v103
	v_div_scale_f32 v77, s[2:3], v76, v76, 1.0
	v_fmac_f32_e32 v104, v105, v102
	v_div_scale_f32 v83, s[2:3], v82, v82, 1.0
	v_fma_f32 v101, -v101, v104, v103
	v_rcp_f32_e32 v66, v65
	v_div_fmas_f32 v101, v101, v102, v104
	v_rcp_f32_e32 v72, v71
	v_div_scale_f32 v109, vcc, 1.0, v106, 1.0
	v_rcp_f32_e32 v78, v77
	v_mul_f32_e32 v110, v109, v108
	v_rcp_f32_e32 v84, v83
	v_fma_f32 v111, -v107, v110, v109
	v_fma_f32 v69, -v65, v66, 1.0
	v_fmac_f32_e32 v110, v111, v108
	v_fma_f32 v75, -v71, v72, 1.0
	v_fma_f32 v107, -v107, v110, v109
	v_fma_f32 v81, -v77, v78, 1.0
	v_div_fmas_f32 v107, v107, v108, v110
	v_fma_f32 v87, -v83, v84, 1.0
	v_fmac_f32_e32 v66, v69, v66
	v_fmac_f32_e32 v72, v75, v72
	v_fmac_f32_e32 v78, v81, v78
	v_fmac_f32_e32 v84, v87, v84
	v_div_fixup_f32 v89, v89, v88, 1.0
	v_div_fixup_f32 v95, v95, v94, 1.0
	v_div_fixup_f32 v101, v101, v100, 1.0
	v_div_fixup_f32 v107, v107, v106, 1.0
	v_mul_f32_e32 v89, v60, v89
	v_mul_f32_e32 v95, v61, v95
	v_mul_f32_e32 v101, v62, v101
	v_mul_f32_e32 v107, v63, v107
	v_mul_f32_e32 v89, v44, v89
	v_mul_f32_e32 v95, v45, v95
	v_mul_f32_e32 v101, v46, v101
	v_mul_f32_e32 v107, v47, v107
	v_cvt_pk_bf16_f32 v89, v89, v89
	v_cvt_pk_bf16_f32 v95, v95, v95
	v_cvt_pk_bf16_f32 v101, v101, v101
	v_cvt_pk_bf16_f32 v107, v107, v107
	ds_write_b16 v112, v89 offset:1536
	ds_write_b16 v112, v95 offset:1600
	ds_write_b16 v112, v101 offset:1664
	ds_write_b16 v112, v107 offset:1728
	ds_read_b128 v[120:123], v113
	ds_read_b128 v[124:127], v113 offset:1024
	v_div_scale_f32 v67, vcc, 1.0, v64, 1.0
	v_mul_f32_e32 v88, 0xbfb8aa3b, v20
	v_mul_f32_e32 v68, v67, v66
	v_mul_f32_e32 v94, 0xbfb8aa3b, v21
	v_fma_f32 v69, -v65, v68, v67
	v_mul_f32_e32 v100, 0xbfb8aa3b, v22
	v_fmac_f32_e32 v68, v69, v66
	v_mul_f32_e32 v106, 0xbfb8aa3b, v23
	v_fma_f32 v65, -v65, v68, v67
	v_exp_f32_e32 v88, v88
	v_div_fmas_f32 v65, v65, v66, v68
	v_exp_f32_e32 v94, v94
	v_div_scale_f32 v73, vcc, 1.0, v70, 1.0
	v_exp_f32_e32 v100, v100
	v_mul_f32_e32 v74, v73, v72
	v_exp_f32_e32 v106, v106
	v_fma_f32 v75, -v71, v74, v73
	v_add_f32_e32 v88, 1.0, v88
	v_fmac_f32_e32 v74, v75, v72
	v_add_f32_e32 v94, 1.0, v94
	v_fma_f32 v71, -v71, v74, v73
	v_add_f32_e32 v100, 1.0, v100
	v_div_fmas_f32 v71, v71, v72, v74
	v_add_f32_e32 v106, 1.0, v106
	v_div_scale_f32 v79, vcc, 1.0, v76, 1.0
	v_div_scale_f32 v89, s[2:3], v88, v88, 1.0
	v_mul_f32_e32 v80, v79, v78
	v_div_scale_f32 v95, s[2:3], v94, v94, 1.0
	v_fma_f32 v81, -v77, v80, v79
	v_div_scale_f32 v101, s[2:3], v100, v100, 1.0
	v_fmac_f32_e32 v80, v81, v78
	v_div_scale_f32 v107, s[2:3], v106, v106, 1.0
	v_fma_f32 v77, -v77, v80, v79
	v_rcp_f32_e32 v90, v89
	v_div_fmas_f32 v77, v77, v78, v80
	v_rcp_f32_e32 v96, v95
	v_div_scale_f32 v85, vcc, 1.0, v82, 1.0
	v_rcp_f32_e32 v102, v101
	v_mul_f32_e32 v86, v85, v84
	v_rcp_f32_e32 v108, v107
	v_fma_f32 v87, -v83, v86, v85
	v_fma_f32 v93, -v89, v90, 1.0
	v_fmac_f32_e32 v86, v87, v84
	v_fma_f32 v99, -v95, v96, 1.0
	v_fma_f32 v83, -v83, v86, v85
	v_fma_f32 v105, -v101, v102, 1.0
	v_div_fmas_f32 v83, v83, v84, v86
	v_fma_f32 v111, -v107, v108, 1.0
	v_fmac_f32_e32 v90, v93, v90
	v_fmac_f32_e32 v96, v99, v96
	v_fmac_f32_e32 v102, v105, v102
	v_fmac_f32_e32 v108, v111, v108
	v_div_fixup_f32 v65, v65, v64, 1.0
	v_div_fixup_f32 v71, v71, v70, 1.0
	v_div_fixup_f32 v77, v77, v76, 1.0
	v_div_fixup_f32 v83, v83, v82, 1.0
	v_mul_f32_e32 v65, v16, v65
	v_mul_f32_e32 v71, v17, v71
	v_mul_f32_e32 v77, v18, v77
	v_mul_f32_e32 v83, v19, v83
	v_mul_f32_e32 v65, v0, v65
	v_mul_f32_e32 v71, v1, v71
	v_mul_f32_e32 v77, v2, v77
	v_mul_f32_e32 v83, v3, v83
	v_cvt_pk_bf16_f32 v65, v65, v65
	v_cvt_pk_bf16_f32 v71, v71, v71
	v_cvt_pk_bf16_f32 v77, v77, v77
	v_cvt_pk_bf16_f32 v83, v83, v83
	ds_write_b16 v112, v65
	ds_write_b16 v112, v71 offset:64
	ds_write_b16 v112, v77 offset:128
	ds_write_b16 v112, v83 offset:192
	v_div_scale_f32 v91, vcc, 1.0, v88, 1.0
	v_mul_f32_e32 v64, 0xbfb8aa3b, v24
	v_mul_f32_e32 v92, v91, v90
	v_mul_f32_e32 v70, 0xbfb8aa3b, v25
	v_fma_f32 v93, -v89, v92, v91
	v_mul_f32_e32 v76, 0xbfb8aa3b, v26
	v_fmac_f32_e32 v92, v93, v90
	v_mul_f32_e32 v82, 0xbfb8aa3b, v27
	v_fma_f32 v89, -v89, v92, v91
	v_exp_f32_e32 v64, v64
	v_div_fmas_f32 v89, v89, v90, v92
	v_exp_f32_e32 v70, v70
	v_div_scale_f32 v97, vcc, 1.0, v94, 1.0
	v_exp_f32_e32 v76, v76
	v_mul_f32_e32 v98, v97, v96
	v_exp_f32_e32 v82, v82
	v_fma_f32 v99, -v95, v98, v97
	v_add_f32_e32 v64, 1.0, v64
	v_fmac_f32_e32 v98, v99, v96
	v_add_f32_e32 v70, 1.0, v70
	v_fma_f32 v95, -v95, v98, v97
	v_add_f32_e32 v76, 1.0, v76
	v_div_fmas_f32 v95, v95, v96, v98
	v_add_f32_e32 v82, 1.0, v82
	v_div_scale_f32 v103, vcc, 1.0, v100, 1.0
	v_div_scale_f32 v65, s[2:3], v64, v64, 1.0
	v_mul_f32_e32 v104, v103, v102
	v_div_scale_f32 v71, s[2:3], v70, v70, 1.0
	v_fma_f32 v105, -v101, v104, v103
	v_div_scale_f32 v77, s[2:3], v76, v76, 1.0
	v_fmac_f32_e32 v104, v105, v102
	v_div_scale_f32 v83, s[2:3], v82, v82, 1.0
	v_fma_f32 v101, -v101, v104, v103
	v_rcp_f32_e32 v66, v65
	v_div_fmas_f32 v101, v101, v102, v104
	v_rcp_f32_e32 v72, v71
	v_div_scale_f32 v109, vcc, 1.0, v106, 1.0
	v_rcp_f32_e32 v78, v77
	v_mul_f32_e32 v110, v109, v108
	v_rcp_f32_e32 v84, v83
	v_fma_f32 v111, -v107, v110, v109
	v_fma_f32 v69, -v65, v66, 1.0
	v_fmac_f32_e32 v110, v111, v108
	v_fma_f32 v75, -v71, v72, 1.0
	v_fma_f32 v107, -v107, v110, v109
	v_fma_f32 v81, -v77, v78, 1.0
	v_div_fmas_f32 v107, v107, v108, v110
	v_fma_f32 v87, -v83, v84, 1.0
	v_fmac_f32_e32 v66, v69, v66
	v_fmac_f32_e32 v72, v75, v72
	v_fmac_f32_e32 v78, v81, v78
	v_fmac_f32_e32 v84, v87, v84
	s_waitcnt lgkmcnt(0)
	global_store_dwordx4 v114, v[120:123], s[98:99]
	s_add_u32 s98, s98, 0x16000
	s_addc_u32 s99, s99, 0
	global_store_dwordx4 v114, v[124:127], s[98:99]
	s_add_u32 s98, s98, 0x16000
	s_addc_u32 s99, s99, 0
	v_div_fixup_f32 v89, v89, v88, 1.0
	v_div_fixup_f32 v95, v95, v94, 1.0
	v_div_fixup_f32 v101, v101, v100, 1.0
	v_div_fixup_f32 v107, v107, v106, 1.0
	v_mul_f32_e32 v89, v20, v89
	v_mul_f32_e32 v95, v21, v95
	v_mul_f32_e32 v101, v22, v101
	v_mul_f32_e32 v107, v23, v107
	v_mul_f32_e32 v89, v4, v89
	v_mul_f32_e32 v95, v5, v95
	v_mul_f32_e32 v101, v6, v101
	v_mul_f32_e32 v107, v7, v107
	v_cvt_pk_bf16_f32 v89, v89, v89
	v_cvt_pk_bf16_f32 v95, v95, v95
	v_cvt_pk_bf16_f32 v101, v101, v101
	v_cvt_pk_bf16_f32 v107, v107, v107
	ds_write_b16 v112, v89 offset:512
	ds_write_b16 v112, v95 offset:576
	ds_write_b16 v112, v101 offset:640
	ds_write_b16 v112, v107 offset:704
	v_div_scale_f32 v67, vcc, 1.0, v64, 1.0
	v_mul_f32_e32 v88, 0xbfb8aa3b, v28
	v_mul_f32_e32 v68, v67, v66
	v_mul_f32_e32 v94, 0xbfb8aa3b, v29
	v_fma_f32 v69, -v65, v68, v67
	v_mul_f32_e32 v100, 0xbfb8aa3b, v30
	v_fmac_f32_e32 v68, v69, v66
	v_mul_f32_e32 v106, 0xbfb8aa3b, v31
	v_fma_f32 v65, -v65, v68, v67
	v_exp_f32_e32 v88, v88
	v_div_fmas_f32 v65, v65, v66, v68
	v_exp_f32_e32 v94, v94
	v_div_scale_f32 v73, vcc, 1.0, v70, 1.0
	v_exp_f32_e32 v100, v100
	v_mul_f32_e32 v74, v73, v72
	v_exp_f32_e32 v106, v106
	v_fma_f32 v75, -v71, v74, v73
	v_add_f32_e32 v88, 1.0, v88
	v_fmac_f32_e32 v74, v75, v72
	v_add_f32_e32 v94, 1.0, v94
	v_fma_f32 v71, -v71, v74, v73
	v_add_f32_e32 v100, 1.0, v100
	v_div_fmas_f32 v71, v71, v72, v74
	v_add_f32_e32 v106, 1.0, v106
	v_div_scale_f32 v79, vcc, 1.0, v76, 1.0
	v_div_scale_f32 v89, s[2:3], v88, v88, 1.0
	v_mul_f32_e32 v80, v79, v78
	v_div_scale_f32 v95, s[2:3], v94, v94, 1.0
	v_fma_f32 v81, -v77, v80, v79
	v_div_scale_f32 v101, s[2:3], v100, v100, 1.0
	v_fmac_f32_e32 v80, v81, v78
	v_div_scale_f32 v107, s[2:3], v106, v106, 1.0
	v_fma_f32 v77, -v77, v80, v79
	v_rcp_f32_e32 v90, v89
	v_div_fmas_f32 v77, v77, v78, v80
	v_rcp_f32_e32 v96, v95
	v_div_scale_f32 v85, vcc, 1.0, v82, 1.0
	v_rcp_f32_e32 v102, v101
	v_mul_f32_e32 v86, v85, v84
	v_rcp_f32_e32 v108, v107
	v_fma_f32 v87, -v83, v86, v85
	v_fma_f32 v93, -v89, v90, 1.0
	v_fmac_f32_e32 v86, v87, v84
	v_fma_f32 v99, -v95, v96, 1.0
	v_fma_f32 v83, -v83, v86, v85
	v_fma_f32 v105, -v101, v102, 1.0
	v_div_fmas_f32 v83, v83, v84, v86
	v_fma_f32 v111, -v107, v108, 1.0
	v_fmac_f32_e32 v90, v93, v90
	v_fmac_f32_e32 v96, v99, v96
	v_fmac_f32_e32 v102, v105, v102
	v_fmac_f32_e32 v108, v111, v108
	v_div_fixup_f32 v65, v65, v64, 1.0
	v_div_fixup_f32 v71, v71, v70, 1.0
	v_div_fixup_f32 v77, v77, v76, 1.0
	v_div_fixup_f32 v83, v83, v82, 1.0
	v_mul_f32_e32 v65, v24, v65
	v_mul_f32_e32 v71, v25, v71
	v_mul_f32_e32 v77, v26, v77
	v_mul_f32_e32 v83, v27, v83
	v_mul_f32_e32 v65, v8, v65
	v_mul_f32_e32 v71, v9, v71
	v_mul_f32_e32 v77, v10, v77
	v_mul_f32_e32 v83, v11, v83
	v_cvt_pk_bf16_f32 v65, v65, v65
	v_cvt_pk_bf16_f32 v71, v71, v71
	v_cvt_pk_bf16_f32 v77, v77, v77
	v_cvt_pk_bf16_f32 v83, v83, v83
	ds_write_b16 v112, v65 offset:1024
	ds_write_b16 v112, v71 offset:1088
	ds_write_b16 v112, v77 offset:1152
	ds_write_b16 v112, v83 offset:1216
	v_div_scale_f32 v91, vcc, 1.0, v88, 1.0
	v_mul_f32_e32 v92, v91, v90
	v_fma_f32 v93, -v89, v92, v91
	v_fmac_f32_e32 v92, v93, v90
	v_fma_f32 v89, -v89, v92, v91
	v_div_fmas_f32 v89, v89, v90, v92
	v_div_scale_f32 v97, vcc, 1.0, v94, 1.0
	v_mul_f32_e32 v98, v97, v96
	v_fma_f32 v99, -v95, v98, v97
	v_fmac_f32_e32 v98, v99, v96
	v_fma_f32 v95, -v95, v98, v97
	v_div_fmas_f32 v95, v95, v96, v98
	v_div_scale_f32 v103, vcc, 1.0, v100, 1.0
	v_mul_f32_e32 v104, v103, v102
	v_fma_f32 v105, -v101, v104, v103
	v_fmac_f32_e32 v104, v105, v102
	v_fma_f32 v101, -v101, v104, v103
	v_div_fmas_f32 v101, v101, v102, v104
	v_div_scale_f32 v109, vcc, 1.0, v106, 1.0
	v_mul_f32_e32 v110, v109, v108
	v_fma_f32 v111, -v107, v110, v109
	v_fmac_f32_e32 v110, v111, v108
	v_fma_f32 v107, -v107, v110, v109
	v_div_fmas_f32 v107, v107, v108, v110
	v_div_fixup_f32 v89, v89, v88, 1.0
	v_div_fixup_f32 v95, v95, v94, 1.0
	v_div_fixup_f32 v101, v101, v100, 1.0
	v_div_fixup_f32 v107, v107, v106, 1.0
	v_mul_f32_e32 v89, v28, v89
	v_mul_f32_e32 v95, v29, v95
	v_mul_f32_e32 v101, v30, v101
	v_mul_f32_e32 v107, v31, v107
	v_mul_f32_e32 v89, v12, v89
	v_mul_f32_e32 v95, v13, v95
	v_mul_f32_e32 v101, v14, v101
	v_mul_f32_e32 v107, v15, v107
	v_cvt_pk_bf16_f32 v89, v89, v89
	v_cvt_pk_bf16_f32 v95, v95, v95
	v_cvt_pk_bf16_f32 v101, v101, v101
	v_cvt_pk_bf16_f32 v107, v107, v107
	ds_write_b16 v112, v89 offset:1536
	ds_write_b16 v112, v95 offset:1600
	ds_write_b16 v112, v101 offset:1664
	ds_write_b16 v112, v107 offset:1728
	ds_read_b128 v[120:123], v113
	ds_read_b128 v[124:127], v113 offset:1024
	s_waitcnt lgkmcnt(0)
	global_store_dwordx4 v114, v[120:123], s[98:99]
	s_add_u32 s98, s98, 0x16000
	s_addc_u32 s99, s99, 0
	global_store_dwordx4 v114, v[124:127], s[98:99]
	s_add_u32 s98, s98, 0x16000
	s_addc_u32 s99, s99, 0
	s_add_i32 s57, s57, s92
	s_cmpk_gt_i32 s57, 0x107f
	s_cbranch_scc1 .LBB0_1043

.LBB0_2283:
	v_lshl_or_b32 v115, v183, 3, v191
	v_lshrrev_b32_e32 v116, 6, v115
	v_and_b32_e32 v117, 63, v115
	v_lshlrev_b32_e32 v113, 11, v116
	v_add_u32_e32 v113, 0x10000, v113
	v_readfirstlane_b32 s100, v116
	v_and_b32_e32 v112, 31, v117
	v_lshl_add_u32 v112, v112, 1, v113
	v_lshrrev_b32_e32 v116, 5, v117
	v_lshl_add_u32 v112, v116, 8, v112
	v_lshl_add_u32 v113, v117, 4, v113
	v_lshrrev_b32_e32 v116, 2, v117
	v_mul_u32_u24_e32 v116, 0x1600, v116
	v_and_b32_e32 v114, 3, v117
	v_lshl_add_u32 v114, v114, 4, v116
	s_lshr_b32 s101, s100, 1
	s_lshl_b32 s101, s101, 6
	s_add_u32 s101, s101, s48
	s_mul_i32 s101, s101, 0x1600
	s_and_b32 s100, s100, 1
	s_lshl_b32 s100, s100, 6
	s_add_u32 s100, s100, s49
	s_add_u32 s101, s101, s100
	s_add_u32 s98, s90, 0x3971900
	s_addc_u32 s99, s91, 0
	s_add_u32 s98, s98, s101
	s_addc_u32 s99, s99, 0
	v_mul_f32_e32 v64, 0xbfb8aa3b, v48
	v_mul_f32_e32 v70, 0xbfb8aa3b, v49
	v_mul_f32_e32 v76, 0xbfb8aa3b, v50
	v_mul_f32_e32 v82, 0xbfb8aa3b, v51
	v_exp_f32_e32 v64, v64
	v_exp_f32_e32 v70, v70
	v_exp_f32_e32 v76, v76
	v_exp_f32_e32 v82, v82
	v_add_f32_e32 v64, 1.0, v64
	v_add_f32_e32 v70, 1.0, v70
	v_add_f32_e32 v76, 1.0, v76
	v_add_f32_e32 v82, 1.0, v82
	v_div_scale_f32 v65, s[4:5], v64, v64, 1.0
	v_div_scale_f32 v71, s[4:5], v70, v70, 1.0
	v_div_scale_f32 v77, s[4:5], v76, v76, 1.0
	v_div_scale_f32 v83, s[4:5], v82, v82, 1.0
	v_rcp_f32_e32 v66, v65
	v_rcp_f32_e32 v72, v71
	v_rcp_f32_e32 v78, v77
	v_rcp_f32_e32 v84, v83
	v_fma_f32 v69, -v65, v66, 1.0
	v_fma_f32 v75, -v71, v72, 1.0
	v_fma_f32 v81, -v77, v78, 1.0
	v_fma_f32 v87, -v83, v84, 1.0
	v_fmac_f32_e32 v66, v69, v66
	v_fmac_f32_e32 v72, v75, v72
	v_fmac_f32_e32 v78, v81, v78
	v_fmac_f32_e32 v84, v87, v84
	v_div_scale_f32 v67, vcc, 1.0, v64, 1.0
	v_mul_f32_e32 v88, 0xbfb8aa3b, v52
	v_mul_f32_e32 v68, v67, v66
	v_mul_f32_e32 v94, 0xbfb8aa3b, v53
	v_fma_f32 v69, -v65, v68, v67
	v_mul_f32_e32 v100, 0xbfb8aa3b, v54
	v_fmac_f32_e32 v68, v69, v66
	v_mul_f32_e32 v106, 0xbfb8aa3b, v55
	v_fma_f32 v65, -v65, v68, v67
	v_exp_f32_e32 v88, v88
	v_div_fmas_f32 v65, v65, v66, v68
	v_exp_f32_e32 v94, v94
	v_div_scale_f32 v73, vcc, 1.0, v70, 1.0
	v_exp_f32_e32 v100, v100
	v_mul_f32_e32 v74, v73, v72
	v_exp_f32_e32 v106, v106
	v_fma_f32 v75, -v71, v74, v73
	v_add_f32_e32 v88, 1.0, v88
	v_fmac_f32_e32 v74, v75, v72
	v_add_f32_e32 v94, 1.0, v94
	v_fma_f32 v71, -v71, v74, v73
	v_add_f32_e32 v100, 1.0, v100
	v_div_fmas_f32 v71, v71, v72, v74
	v_add_f32_e32 v106, 1.0, v106
	v_div_scale_f32 v79, vcc, 1.0, v76, 1.0
	v_div_scale_f32 v89, s[4:5], v88, v88, 1.0
	v_mul_f32_e32 v80, v79, v78
	v_div_scale_f32 v95, s[4:5], v94, v94, 1.0
	v_fma_f32 v81, -v77, v80, v79
	v_div_scale_f32 v101, s[4:5], v100, v100, 1.0
	v_fmac_f32_e32 v80, v81, v78
	v_div_scale_f32 v107, s[4:5], v106, v106, 1.0
	v_fma_f32 v77, -v77, v80, v79
	v_rcp_f32_e32 v90, v89
	v_div_fmas_f32 v77, v77, v78, v80
	v_rcp_f32_e32 v96, v95
	v_div_scale_f32 v85, vcc, 1.0, v82, 1.0
	v_rcp_f32_e32 v102, v101
	v_mul_f32_e32 v86, v85, v84
	v_rcp_f32_e32 v108, v107
	v_fma_f32 v87, -v83, v86, v85
	v_fma_f32 v93, -v89, v90, 1.0
	v_fmac_f32_e32 v86, v87, v84
	v_fma_f32 v99, -v95, v96, 1.0
	v_fma_f32 v83, -v83, v86, v85
	v_fma_f32 v105, -v101, v102, 1.0
	v_div_fmas_f32 v83, v83, v84, v86
	v_fma_f32 v111, -v107, v108, 1.0
	v_fmac_f32_e32 v90, v93, v90
	v_fmac_f32_e32 v96, v99, v96
	v_fmac_f32_e32 v102, v105, v102
	v_fmac_f32_e32 v108, v111, v108
	v_div_fixup_f32 v65, v65, v64, 1.0
	v_div_fixup_f32 v71, v71, v70, 1.0
	v_div_fixup_f32 v77, v77, v76, 1.0
	v_div_fixup_f32 v83, v83, v82, 1.0
	v_mul_f32_e32 v65, v48, v65
	v_mul_f32_e32 v71, v49, v71
	v_mul_f32_e32 v77, v50, v77
	v_mul_f32_e32 v83, v51, v83
	v_mul_f32_e32 v65, v32, v65
	v_mul_f32_e32 v71, v33, v71
	v_mul_f32_e32 v77, v34, v77
	v_mul_f32_e32 v83, v35, v83
	v_cvt_pk_bf16_f32 v65, v65, v65
	v_cvt_pk_bf16_f32 v71, v71, v71
	v_cvt_pk_bf16_f32 v77, v77, v77
	v_cvt_pk_bf16_f32 v83, v83, v83
	ds_write_b16 v112, v65
	ds_write_b16 v112, v71 offset:64
	ds_write_b16 v112, v77 offset:128
	ds_write_b16 v112, v83 offset:192
	v_div_scale_f32 v91, vcc, 1.0, v88, 1.0
	v_mul_f32_e32 v64, 0xbfb8aa3b, v56
	v_mul_f32_e32 v92, v91, v90
	v_mul_f32_e32 v70, 0xbfb8aa3b, v57
	v_fma_f32 v93, -v89, v92, v91
	v_mul_f32_e32 v76, 0xbfb8aa3b, v58
	v_fmac_f32_e32 v92, v93, v90
	v_mul_f32_e32 v82, 0xbfb8aa3b, v59
	v_fma_f32 v89, -v89, v92, v91
	v_exp_f32_e32 v64, v64
	v_div_fmas_f32 v89, v89, v90, v92
	v_exp_f32_e32 v70, v70
	v_div_scale_f32 v97, vcc, 1.0, v94, 1.0
	v_exp_f32_e32 v76, v76
	v_mul_f32_e32 v98, v97, v96
	v_exp_f32_e32 v82, v82
	v_fma_f32 v99, -v95, v98, v97
	v_add_f32_e32 v64, 1.0, v64
	v_fmac_f32_e32 v98, v99, v96
	v_add_f32_e32 v70, 1.0, v70
	v_fma_f32 v95, -v95, v98, v97
	v_add_f32_e32 v76, 1.0, v76
	v_div_fmas_f32 v95, v95, v96, v98
	v_add_f32_e32 v82, 1.0, v82
	v_div_scale_f32 v103, vcc, 1.0, v100, 1.0
	v_div_scale_f32 v65, s[4:5], v64, v64, 1.0
	v_mul_f32_e32 v104, v103, v102
	v_div_scale_f32 v71, s[4:5], v70, v70, 1.0
	v_fma_f32 v105, -v101, v104, v103
	v_div_scale_f32 v77, s[4:5], v76, v76, 1.0
	v_fmac_f32_e32 v104, v105, v102
	v_div_scale_f32 v83, s[4:5], v82, v82, 1.0
	v_fma_f32 v101, -v101, v104, v103
	v_rcp_f32_e32 v66, v65
	v_div_fmas_f32 v101, v101, v102, v104
	v_rcp_f32_e32 v72, v71
	v_div_scale_f32 v109, vcc, 1.0, v106, 1.0
	v_rcp_f32_e32 v78, v77
	v_mul_f32_e32 v110, v109, v108
	v_rcp_f32_e32 v84, v83
	v_fma_f32 v111, -v107, v110, v109
	v_fma_f32 v69, -v65, v66, 1.0
	v_fmac_f32_e32 v110, v111, v108
	v_fma_f32 v75, -v71, v72, 1.0
	v_fma_f32 v107, -v107, v110, v109
	v_fma_f32 v81, -v77, v78, 1.0
	v_div_fmas_f32 v107, v107, v108, v110
	v_fma_f32 v87, -v83, v84, 1.0
	v_fmac_f32_e32 v66, v69, v66
	v_fmac_f32_e32 v72, v75, v72
	v_fmac_f32_e32 v78, v81, v78
	v_fmac_f32_e32 v84, v87, v84
	v_div_fixup_f32 v89, v89, v88, 1.0
	v_div_fixup_f32 v95, v95, v94, 1.0
	v_div_fixup_f32 v101, v101, v100, 1.0
	v_div_fixup_f32 v107, v107, v106, 1.0
	v_mul_f32_e32 v89, v52, v89
	v_mul_f32_e32 v95, v53, v95
	v_mul_f32_e32 v101, v54, v101
	v_mul_f32_e32 v107, v55, v107
	v_mul_f32_e32 v89, v36, v89
	v_mul_f32_e32 v95, v37, v95
	v_mul_f32_e32 v101, v38, v101
	v_mul_f32_e32 v107, v39, v107
	v_cvt_pk_bf16_f32 v89, v89, v89
	v_cvt_pk_bf16_f32 v95, v95, v95
	v_cvt_pk_bf16_f32 v101, v101, v101
	v_cvt_pk_bf16_f32 v107, v107, v107
	ds_write_b16 v112, v89 offset:512
	ds_write_b16 v112, v95 offset:576
	ds_write_b16 v112, v101 offset:640
	ds_write_b16 v112, v107 offset:704
	v_div_scale_f32 v67, vcc, 1.0, v64, 1.0
	v_mul_f32_e32 v88, 0xbfb8aa3b, v60
	v_mul_f32_e32 v68, v67, v66
	v_mul_f32_e32 v94, 0xbfb8aa3b, v61
	v_fma_f32 v69, -v65, v68, v67
	v_mul_f32_e32 v100, 0xbfb8aa3b, v62
	v_fmac_f32_e32 v68, v69, v66
	v_mul_f32_e32 v106, 0xbfb8aa3b, v63
	v_fma_f32 v65, -v65, v68, v67
	v_exp_f32_e32 v88, v88
	v_div_fmas_f32 v65, v65, v66, v68
	v_exp_f32_e32 v94, v94
	v_div_scale_f32 v73, vcc, 1.0, v70, 1.0
	v_exp_f32_e32 v100, v100
	v_mul_f32_e32 v74, v73, v72
	v_exp_f32_e32 v106, v106
	v_fma_f32 v75, -v71, v74, v73
	v_add_f32_e32 v88, 1.0, v88
	v_fmac_f32_e32 v74, v75, v72
	v_add_f32_e32 v94, 1.0, v94
	v_fma_f32 v71, -v71, v74, v73
	v_add_f32_e32 v100, 1.0, v100
	v_div_fmas_f32 v71, v71, v72, v74
	v_add_f32_e32 v106, 1.0, v106
	v_div_scale_f32 v79, vcc, 1.0, v76, 1.0
	v_div_scale_f32 v89, s[4:5], v88, v88, 1.0
	v_mul_f32_e32 v80, v79, v78
	v_div_scale_f32 v95, s[4:5], v94, v94, 1.0
	v_fma_f32 v81, -v77, v80, v79
	v_div_scale_f32 v101, s[4:5], v100, v100, 1.0
	v_fmac_f32_e32 v80, v81, v78
	v_div_scale_f32 v107, s[4:5], v106, v106, 1.0
	v_fma_f32 v77, -v77, v80, v79
	v_rcp_f32_e32 v90, v89
	v_div_fmas_f32 v77, v77, v78, v80
	v_rcp_f32_e32 v96, v95
	v_div_scale_f32 v85, vcc, 1.0, v82, 1.0
	v_rcp_f32_e32 v102, v101
	v_mul_f32_e32 v86, v85, v84
	v_rcp_f32_e32 v108, v107
	v_fma_f32 v87, -v83, v86, v85
	v_fma_f32 v93, -v89, v90, 1.0
	v_fmac_f32_e32 v86, v87, v84
	v_fma_f32 v99, -v95, v96, 1.0
	v_fma_f32 v83, -v83, v86, v85
	v_fma_f32 v105, -v101, v102, 1.0
	v_div_fmas_f32 v83, v83, v84, v86
	v_fma_f32 v111, -v107, v108, 1.0
	v_fmac_f32_e32 v90, v93, v90
	v_fmac_f32_e32 v96, v99, v96
	v_fmac_f32_e32 v102, v105, v102
	v_fmac_f32_e32 v108, v111, v108
	v_div_fixup_f32 v65, v65, v64, 1.0
	v_div_fixup_f32 v71, v71, v70, 1.0
	v_div_fixup_f32 v77, v77, v76, 1.0
	v_div_fixup_f32 v83, v83, v82, 1.0
	v_mul_f32_e32 v65, v56, v65
	v_mul_f32_e32 v71, v57, v71
	v_mul_f32_e32 v77, v58, v77
	v_mul_f32_e32 v83, v59, v83
	v_mul_f32_e32 v65, v40, v65
	v_mul_f32_e32 v71, v41, v71
	v_mul_f32_e32 v77, v42, v77
	v_mul_f32_e32 v83, v43, v83
	v_cvt_pk_bf16_f32 v65, v65, v65
	v_cvt_pk_bf16_f32 v71, v71, v71
	v_cvt_pk_bf16_f32 v77, v77, v77
	v_cvt_pk_bf16_f32 v83, v83, v83
	ds_write_b16 v112, v65 offset:1024
	ds_write_b16 v112, v71 offset:1088
	ds_write_b16 v112, v77 offset:1152
	ds_write_b16 v112, v83 offset:1216
	v_div_scale_f32 v91, vcc, 1.0, v88, 1.0
	v_mul_f32_e32 v64, 0xbfb8aa3b, v16
	v_mul_f32_e32 v92, v91, v90
	v_mul_f32_e32 v70, 0xbfb8aa3b, v17
	v_fma_f32 v93, -v89, v92, v91
	v_mul_f32_e32 v76, 0xbfb8aa3b, v18
	v_fmac_f32_e32 v92, v93, v90
	v_mul_f32_e32 v82, 0xbfb8aa3b, v19
	v_fma_f32 v89, -v89, v92, v91
	v_exp_f32_e32 v64, v64
	v_div_fmas_f32 v89, v89, v90, v92
	v_exp_f32_e32 v70, v70
	v_div_scale_f32 v97, vcc, 1.0, v94, 1.0
	v_exp_f32_e32 v76, v76
	v_mul_f32_e32 v98, v97, v96
	v_exp_f32_e32 v82, v82
	v_fma_f32 v99, -v95, v98, v97
	v_add_f32_e32 v64, 1.0, v64
	v_fmac_f32_e32 v98, v99, v96
	v_add_f32_e32 v70, 1.0, v70
	v_fma_f32 v95, -v95, v98, v97
	v_add_f32_e32 v76, 1.0, v76
	v_div_fmas_f32 v95, v95, v96, v98
	v_add_f32_e32 v82, 1.0, v82
	v_div_scale_f32 v103, vcc, 1.0, v100, 1.0
	v_div_scale_f32 v65, s[4:5], v64, v64, 1.0
	v_mul_f32_e32 v104, v103, v102
	v_div_scale_f32 v71, s[4:5], v70, v70, 1.0
	v_fma_f32 v105, -v101, v104, v103
	v_div_scale_f32 v77, s[4:5], v76, v76, 1.0
	v_fmac_f32_e32 v104, v105, v102
	v_div_scale_f32 v83, s[4:5], v82, v82, 1.0
	v_fma_f32 v101, -v101, v104, v103
	v_rcp_f32_e32 v66, v65
	v_div_fmas_f32 v101, v101, v102, v104
	v_rcp_f32_e32 v72, v71
	v_div_scale_f32 v109, vcc, 1.0, v106, 1.0
	v_rcp_f32_e32 v78, v77
	v_mul_f32_e32 v110, v109, v108
	v_rcp_f32_e32 v84, v83
	v_fma_f32 v111, -v107, v110, v109
	v_fma_f32 v69, -v65, v66, 1.0
	v_fmac_f32_e32 v110, v111, v108
	v_fma_f32 v75, -v71, v72, 1.0
	v_fma_f32 v107, -v107, v110, v109
	v_fma_f32 v81, -v77, v78, 1.0
	v_div_fmas_f32 v107, v107, v108, v110
	v_fma_f32 v87, -v83, v84, 1.0
	v_fmac_f32_e32 v66, v69, v66
	v_fmac_f32_e32 v72, v75, v72
	v_fmac_f32_e32 v78, v81, v78
	v_fmac_f32_e32 v84, v87, v84
	v_div_fixup_f32 v89, v89, v88, 1.0
	v_div_fixup_f32 v95, v95, v94, 1.0
	v_div_fixup_f32 v101, v101, v100, 1.0
	v_div_fixup_f32 v107, v107, v106, 1.0
	v_mul_f32_e32 v89, v60, v89
	v_mul_f32_e32 v95, v61, v95
	v_mul_f32_e32 v101, v62, v101
	v_mul_f32_e32 v107, v63, v107
	v_mul_f32_e32 v89, v44, v89
	v_mul_f32_e32 v95, v45, v95
	v_mul_f32_e32 v101, v46, v101
	v_mul_f32_e32 v107, v47, v107
	v_cvt_pk_bf16_f32 v89, v89, v89
	v_cvt_pk_bf16_f32 v95, v95, v95
	v_cvt_pk_bf16_f32 v101, v101, v101
	v_cvt_pk_bf16_f32 v107, v107, v107
	ds_write_b16 v112, v89 offset:1536
	ds_write_b16 v112, v95 offset:1600
	ds_write_b16 v112, v101 offset:1664
	ds_write_b16 v112, v107 offset:1728
	ds_read_b128 v[120:123], v113
	ds_read_b128 v[124:127], v113 offset:1024
	v_div_scale_f32 v67, vcc, 1.0, v64, 1.0
	v_mul_f32_e32 v88, 0xbfb8aa3b, v20
	v_mul_f32_e32 v68, v67, v66
	v_mul_f32_e32 v94, 0xbfb8aa3b, v21
	v_fma_f32 v69, -v65, v68, v67
	v_mul_f32_e32 v100, 0xbfb8aa3b, v22
	v_fmac_f32_e32 v68, v69, v66
	v_mul_f32_e32 v106, 0xbfb8aa3b, v23
	v_fma_f32 v65, -v65, v68, v67
	v_exp_f32_e32 v88, v88
	v_div_fmas_f32 v65, v65, v66, v68
	v_exp_f32_e32 v94, v94
	v_div_scale_f32 v73, vcc, 1.0, v70, 1.0
	v_exp_f32_e32 v100, v100
	v_mul_f32_e32 v74, v73, v72
	v_exp_f32_e32 v106, v106
	v_fma_f32 v75, -v71, v74, v73
	v_add_f32_e32 v88, 1.0, v88
	v_fmac_f32_e32 v74, v75, v72
	v_add_f32_e32 v94, 1.0, v94
	v_fma_f32 v71, -v71, v74, v73
	v_add_f32_e32 v100, 1.0, v100
	v_div_fmas_f32 v71, v71, v72, v74
	v_add_f32_e32 v106, 1.0, v106
	v_div_scale_f32 v79, vcc, 1.0, v76, 1.0
	v_div_scale_f32 v89, s[4:5], v88, v88, 1.0
	v_mul_f32_e32 v80, v79, v78
	v_div_scale_f32 v95, s[4:5], v94, v94, 1.0
	v_fma_f32 v81, -v77, v80, v79
	v_div_scale_f32 v101, s[4:5], v100, v100, 1.0
	v_fmac_f32_e32 v80, v81, v78
	v_div_scale_f32 v107, s[4:5], v106, v106, 1.0
	v_fma_f32 v77, -v77, v80, v79
	v_rcp_f32_e32 v90, v89
	v_div_fmas_f32 v77, v77, v78, v80
	v_rcp_f32_e32 v96, v95
	v_div_scale_f32 v85, vcc, 1.0, v82, 1.0
	v_rcp_f32_e32 v102, v101
	v_mul_f32_e32 v86, v85, v84
	v_rcp_f32_e32 v108, v107
	v_fma_f32 v87, -v83, v86, v85
	v_fma_f32 v93, -v89, v90, 1.0
	v_fmac_f32_e32 v86, v87, v84
	v_fma_f32 v99, -v95, v96, 1.0
	v_fma_f32 v83, -v83, v86, v85
	v_fma_f32 v105, -v101, v102, 1.0
	v_div_fmas_f32 v83, v83, v84, v86
	v_fma_f32 v111, -v107, v108, 1.0
	v_fmac_f32_e32 v90, v93, v90
	v_fmac_f32_e32 v96, v99, v96
	v_fmac_f32_e32 v102, v105, v102
	v_fmac_f32_e32 v108, v111, v108
	v_div_fixup_f32 v65, v65, v64, 1.0
	v_div_fixup_f32 v71, v71, v70, 1.0
	v_div_fixup_f32 v77, v77, v76, 1.0
	v_div_fixup_f32 v83, v83, v82, 1.0
	v_mul_f32_e32 v65, v16, v65
	v_mul_f32_e32 v71, v17, v71
	v_mul_f32_e32 v77, v18, v77
	v_mul_f32_e32 v83, v19, v83
	v_mul_f32_e32 v65, v0, v65
	v_mul_f32_e32 v71, v1, v71
	v_mul_f32_e32 v77, v2, v77
	v_mul_f32_e32 v83, v3, v83
	v_cvt_pk_bf16_f32 v65, v65, v65
	v_cvt_pk_bf16_f32 v71, v71, v71
	v_cvt_pk_bf16_f32 v77, v77, v77
	v_cvt_pk_bf16_f32 v83, v83, v83
	ds_write_b16 v112, v65
	ds_write_b16 v112, v71 offset:64
	ds_write_b16 v112, v77 offset:128
	ds_write_b16 v112, v83 offset:192
	v_div_scale_f32 v91, vcc, 1.0, v88, 1.0
	v_mul_f32_e32 v64, 0xbfb8aa3b, v24
	v_mul_f32_e32 v92, v91, v90
	v_mul_f32_e32 v70, 0xbfb8aa3b, v25
	v_fma_f32 v93, -v89, v92, v91
	v_mul_f32_e32 v76, 0xbfb8aa3b, v26
	v_fmac_f32_e32 v92, v93, v90
	v_mul_f32_e32 v82, 0xbfb8aa3b, v27
	v_fma_f32 v89, -v89, v92, v91
	v_exp_f32_e32 v64, v64
	v_div_fmas_f32 v89, v89, v90, v92
	v_exp_f32_e32 v70, v70
	v_div_scale_f32 v97, vcc, 1.0, v94, 1.0
	v_exp_f32_e32 v76, v76
	v_mul_f32_e32 v98, v97, v96
	v_exp_f32_e32 v82, v82
	v_fma_f32 v99, -v95, v98, v97
	v_add_f32_e32 v64, 1.0, v64
	v_fmac_f32_e32 v98, v99, v96
	v_add_f32_e32 v70, 1.0, v70
	v_fma_f32 v95, -v95, v98, v97
	v_add_f32_e32 v76, 1.0, v76
	v_div_fmas_f32 v95, v95, v96, v98
	v_add_f32_e32 v82, 1.0, v82
	v_div_scale_f32 v103, vcc, 1.0, v100, 1.0
	v_div_scale_f32 v65, s[4:5], v64, v64, 1.0
	v_mul_f32_e32 v104, v103, v102
	v_div_scale_f32 v71, s[4:5], v70, v70, 1.0
	v_fma_f32 v105, -v101, v104, v103
	v_div_scale_f32 v77, s[4:5], v76, v76, 1.0
	v_fmac_f32_e32 v104, v105, v102
	v_div_scale_f32 v83, s[4:5], v82, v82, 1.0
	v_fma_f32 v101, -v101, v104, v103
	v_rcp_f32_e32 v66, v65
	v_div_fmas_f32 v101, v101, v102, v104
	v_rcp_f32_e32 v72, v71
	v_div_scale_f32 v109, vcc, 1.0, v106, 1.0
	v_rcp_f32_e32 v78, v77
	v_mul_f32_e32 v110, v109, v108
	v_rcp_f32_e32 v84, v83
	v_fma_f32 v111, -v107, v110, v109
	v_fma_f32 v69, -v65, v66, 1.0
	v_fmac_f32_e32 v110, v111, v108
	v_fma_f32 v75, -v71, v72, 1.0
	v_fma_f32 v107, -v107, v110, v109
	v_fma_f32 v81, -v77, v78, 1.0
	v_div_fmas_f32 v107, v107, v108, v110
	v_fma_f32 v87, -v83, v84, 1.0
	v_fmac_f32_e32 v66, v69, v66
	v_fmac_f32_e32 v72, v75, v72
	v_fmac_f32_e32 v78, v81, v78
	v_fmac_f32_e32 v84, v87, v84
	s_waitcnt lgkmcnt(0)
	global_store_dwordx4 v114, v[120:123], s[98:99]
	s_add_u32 s98, s98, 0x16000
	s_addc_u32 s99, s99, 0
	global_store_dwordx4 v114, v[124:127], s[98:99]
	s_add_u32 s98, s98, 0x16000
	s_addc_u32 s99, s99, 0
	v_div_fixup_f32 v89, v89, v88, 1.0
	v_div_fixup_f32 v95, v95, v94, 1.0
	v_div_fixup_f32 v101, v101, v100, 1.0
	v_div_fixup_f32 v107, v107, v106, 1.0
	v_mul_f32_e32 v89, v20, v89
	v_mul_f32_e32 v95, v21, v95
	v_mul_f32_e32 v101, v22, v101
	v_mul_f32_e32 v107, v23, v107
	v_mul_f32_e32 v89, v4, v89
	v_mul_f32_e32 v95, v5, v95
	v_mul_f32_e32 v101, v6, v101
	v_mul_f32_e32 v107, v7, v107
	v_cvt_pk_bf16_f32 v89, v89, v89
	v_cvt_pk_bf16_f32 v95, v95, v95
	v_cvt_pk_bf16_f32 v101, v101, v101
	v_cvt_pk_bf16_f32 v107, v107, v107
	ds_write_b16 v112, v89 offset:512
	ds_write_b16 v112, v95 offset:576
	ds_write_b16 v112, v101 offset:640
	ds_write_b16 v112, v107 offset:704
	v_div_scale_f32 v67, vcc, 1.0, v64, 1.0
	v_mul_f32_e32 v88, 0xbfb8aa3b, v28
	v_mul_f32_e32 v68, v67, v66
	v_mul_f32_e32 v94, 0xbfb8aa3b, v29
	v_fma_f32 v69, -v65, v68, v67
	v_mul_f32_e32 v100, 0xbfb8aa3b, v30
	v_fmac_f32_e32 v68, v69, v66
	v_mul_f32_e32 v106, 0xbfb8aa3b, v31
	v_fma_f32 v65, -v65, v68, v67
	v_exp_f32_e32 v88, v88
	v_div_fmas_f32 v65, v65, v66, v68
	v_exp_f32_e32 v94, v94
	v_div_scale_f32 v73, vcc, 1.0, v70, 1.0
	v_exp_f32_e32 v100, v100
	v_mul_f32_e32 v74, v73, v72
	v_exp_f32_e32 v106, v106
	v_fma_f32 v75, -v71, v74, v73
	v_add_f32_e32 v88, 1.0, v88
	v_fmac_f32_e32 v74, v75, v72
	v_add_f32_e32 v94, 1.0, v94
	v_fma_f32 v71, -v71, v74, v73
	v_add_f32_e32 v100, 1.0, v100
	v_div_fmas_f32 v71, v71, v72, v74
	v_add_f32_e32 v106, 1.0, v106
	v_div_scale_f32 v79, vcc, 1.0, v76, 1.0
	v_div_scale_f32 v89, s[4:5], v88, v88, 1.0
	v_mul_f32_e32 v80, v79, v78
	v_div_scale_f32 v95, s[4:5], v94, v94, 1.0
	v_fma_f32 v81, -v77, v80, v79
	v_div_scale_f32 v101, s[4:5], v100, v100, 1.0
	v_fmac_f32_e32 v80, v81, v78
	v_div_scale_f32 v107, s[4:5], v106, v106, 1.0
	v_fma_f32 v77, -v77, v80, v79
	v_rcp_f32_e32 v90, v89
	v_div_fmas_f32 v77, v77, v78, v80
	v_rcp_f32_e32 v96, v95
	v_div_scale_f32 v85, vcc, 1.0, v82, 1.0
	v_rcp_f32_e32 v102, v101
	v_mul_f32_e32 v86, v85, v84
	v_rcp_f32_e32 v108, v107
	v_fma_f32 v87, -v83, v86, v85
	v_fma_f32 v93, -v89, v90, 1.0
	v_fmac_f32_e32 v86, v87, v84
	v_fma_f32 v99, -v95, v96, 1.0
	v_fma_f32 v83, -v83, v86, v85
	v_fma_f32 v105, -v101, v102, 1.0
	v_div_fmas_f32 v83, v83, v84, v86
	v_fma_f32 v111, -v107, v108, 1.0
	v_fmac_f32_e32 v90, v93, v90
	v_fmac_f32_e32 v96, v99, v96
	v_fmac_f32_e32 v102, v105, v102
	v_fmac_f32_e32 v108, v111, v108
	v_div_fixup_f32 v65, v65, v64, 1.0
	v_div_fixup_f32 v71, v71, v70, 1.0
	v_div_fixup_f32 v77, v77, v76, 1.0
	v_div_fixup_f32 v83, v83, v82, 1.0
	v_mul_f32_e32 v65, v24, v65
	v_mul_f32_e32 v71, v25, v71
	v_mul_f32_e32 v77, v26, v77
	v_mul_f32_e32 v83, v27, v83
	v_mul_f32_e32 v65, v8, v65
	v_mul_f32_e32 v71, v9, v71
	v_mul_f32_e32 v77, v10, v77
	v_mul_f32_e32 v83, v11, v83
	v_cvt_pk_bf16_f32 v65, v65, v65
	v_cvt_pk_bf16_f32 v71, v71, v71
	v_cvt_pk_bf16_f32 v77, v77, v77
	v_cvt_pk_bf16_f32 v83, v83, v83
	ds_write_b16 v112, v65 offset:1024
	ds_write_b16 v112, v71 offset:1088
	ds_write_b16 v112, v77 offset:1152
	ds_write_b16 v112, v83 offset:1216
	v_div_scale_f32 v91, vcc, 1.0, v88, 1.0
	v_mul_f32_e32 v92, v91, v90
	v_fma_f32 v93, -v89, v92, v91
	v_fmac_f32_e32 v92, v93, v90
	v_fma_f32 v89, -v89, v92, v91
	v_div_fmas_f32 v89, v89, v90, v92
	v_div_scale_f32 v97, vcc, 1.0, v94, 1.0
	v_mul_f32_e32 v98, v97, v96
	v_fma_f32 v99, -v95, v98, v97
	v_fmac_f32_e32 v98, v99, v96
	v_fma_f32 v95, -v95, v98, v97
	v_div_fmas_f32 v95, v95, v96, v98
	v_div_scale_f32 v103, vcc, 1.0, v100, 1.0
	v_mul_f32_e32 v104, v103, v102
	v_fma_f32 v105, -v101, v104, v103
	v_fmac_f32_e32 v104, v105, v102
	v_fma_f32 v101, -v101, v104, v103
	v_div_fmas_f32 v101, v101, v102, v104
	v_div_scale_f32 v109, vcc, 1.0, v106, 1.0
	v_mul_f32_e32 v110, v109, v108
	v_fma_f32 v111, -v107, v110, v109
	v_fmac_f32_e32 v110, v111, v108
	v_fma_f32 v107, -v107, v110, v109
	v_div_fmas_f32 v107, v107, v108, v110
	v_div_fixup_f32 v89, v89, v88, 1.0
	v_div_fixup_f32 v95, v95, v94, 1.0
	v_div_fixup_f32 v101, v101, v100, 1.0
	v_div_fixup_f32 v107, v107, v106, 1.0
	v_mul_f32_e32 v89, v28, v89
	v_mul_f32_e32 v95, v29, v95
	v_mul_f32_e32 v101, v30, v101
	v_mul_f32_e32 v107, v31, v107
	v_mul_f32_e32 v89, v12, v89
	v_mul_f32_e32 v95, v13, v95
	v_mul_f32_e32 v101, v14, v101
	v_mul_f32_e32 v107, v15, v107
	v_cvt_pk_bf16_f32 v89, v89, v89
	v_cvt_pk_bf16_f32 v95, v95, v95
	v_cvt_pk_bf16_f32 v101, v101, v101
	v_cvt_pk_bf16_f32 v107, v107, v107
	ds_write_b16 v112, v89 offset:1536
	ds_write_b16 v112, v95 offset:1600
	ds_write_b16 v112, v101 offset:1664
	ds_write_b16 v112, v107 offset:1728
	ds_read_b128 v[120:123], v113
	ds_read_b128 v[124:127], v113 offset:1024
	s_waitcnt lgkmcnt(0)
	global_store_dwordx4 v114, v[120:123], s[98:99]
	s_add_u32 s98, s98, 0x16000
	s_addc_u32 s99, s99, 0
	global_store_dwordx4 v114, v[124:127], s[98:99]
	s_add_u32 s98, s98, 0x16000
	s_addc_u32 s99, s99, 0
	s_add_i32 s47, s47, s92
	s_cmpk_gt_i32 s47, 0x107f
	s_cbranch_scc1 .LBB0_2292
